# v14 + one static s_setprio 1 for waves 4-7 (younger half) for the attention phase, reset to 0 after it
# baseline (speedup 1.0000x reference)
.LBB0_729:
	s_or_b64 exec, exec, s[8:9]
	s_mov_b64 s[10:11], s[96:97]
	s_waitcnt lgkmcnt(0)
	s_barrier
	v_readfirstlane_b32 s76, v193
	s_nop 3
	s_lshr_b32 s76, s76, 6
	s_cmp_ge_u32 s76, 4
	s_cbranch_scc0 .Lnoprio_att
	s_setprio 1
.Lnoprio_att:
	s_load_dwordx2 s[76:77], s[10:11], 0x98
	v_mov_b32_e32 v0, v193
	s_nop 0
	v_cmp_gt_i32_e32 vcc, 48, v0
	s_and_saveexec_b64 s[8:9], vcc
	s_cbranch_execz .LBB0_731
	s_load_dwordx2 s[2:3], s[10:11], 0x80
	v_readlane_b32 s4, v255, 46
	s_mul_i32 s92, s4, 0xc0
	s_lshl_b64 s[10:11], s[92:93], 2
	v_ashrrev_i32_e32 v1, 31, v0
	s_waitcnt lgkmcnt(0)
	s_add_u32 s2, s2, s10
	s_addc_u32 s3, s3, s11
	v_lshl_add_u64 v[2:3], v[0:1], 4, s[2:3]
	global_load_dwordx4 v[2:5], v[2:3], off
	v_lshl_add_u32 v0, v0, 4, 0
	v_add_u32_e32 v0, 0x1e800, v0
	s_waitcnt vmcnt(0)
	ds_write_b128 v0, v[2:5]

.LBB0_836:
	s_or_b64 exec, exec, s[8:9]
	s_mov_b64 s[10:11], s[96:97]
	s_waitcnt lgkmcnt(0)
	s_barrier
	s_setprio 0
	s_load_dwordx2 s[8:9], s[10:11], 0x98
	v_readlane_b32 s2, v255, 13
	v_readlane_b32 s3, v255, 14
	v_readlane_b32 s91, v255, 6
	s_movk_i32 s90, 0x61
	v_mov_b32_e32 v0, v193
	s_mov_b64 s[12:13], -1
	s_and_b64 vcc, exec, s[2:3]
	s_cbranch_vccz .LBB0_838
	s_load_dwordx2 s[16:17], s[10:11], 0x90
	s_mov_b64 s[12:13], 0
